# GEMM K-loops of P1, P9, P10: 14 of 16 LDS-DMA loads per iteration use SGPR base + 32-bit VGPR offset (no 64-bit VALU address adds); one 4-byte pad at the P2 entry restores the code-placement phase of
# speedup vs baseline: 1.0198x; 1.0036x over previous
.LBB0_282:
	ds_read_b128 v[128:131], v175
	ds_read_b128 v[132:135], v175 offset:1024
	ds_read_b128 v[154:157], v175 offset:2048
	ds_read_b128 v[158:161], v175 offset:3072
	ds_read_b128 v[162:165], v176
	ds_read_b128 v[166:169], v176 offset:1024
	ds_read_b128 v[170:173], v176 offset:2048
	ds_read_b128 v[180:183], v176 offset:3072
	s_add_i32 s85, s28, 2
	s_add_u32 s29, s10, 0xfffc0080
	s_addc_u32 s36, s11, -1
	s_cmp_eq_u32 s68, s28
	s_cselect_b32 s28, s78, s79
	s_cselect_b32 s37, s7, s36
	s_cselect_b32 s36, s49, s29
	s_cselect_b32 s29, s51, s84
	v_lshl_add_u64 v[188:189], s[10:11], 0, v[146:147]
	s_add_i32 m0, s57, 0xc000
	ds_read_b128 v[184:187], v177
	ds_read_b128 v[192:195], v177 offset:1024
	ds_read_b128 v[196:199], v177 offset:2048
	ds_read_b128 v[200:203], v177 offset:3072
	ds_read_b128 v[204:207], v177 offset:4096
	ds_read_b128 v[208:211], v177 offset:5120
	ds_read_b128 v[212:215], v177 offset:6144
	ds_read_b128 v[216:219], v177 offset:7168
	global_load_lds_dwordx4 v[188:189], off
	v_lshl_add_u64 v[188:189], s[10:11], 0, v[148:149]
	s_add_i32 m0, s57, 0xe000
	s_nop 0
	global_load_lds_dwordx4 v[188:189], off
	s_waitcnt vmcnt(8)
	s_waitcnt lgkmcnt(0)
	s_barrier
	s_setprio 1
	s_waitcnt lgkmcnt(0)
	v_mfma_f32_16x16x32_bf16 v[124:127], v[128:131], v[184:187], v[124:127]
	v_mfma_f32_16x16x32_bf16 v[120:123], v[154:157], v[184:187], v[120:123]
	v_mfma_f32_16x16x32_bf16 v[116:119], v[128:131], v[196:199], v[116:119]
	v_mfma_f32_16x16x32_bf16 v[112:115], v[154:157], v[196:199], v[112:115]
	v_mfma_f32_16x16x32_bf16 v[108:111], v[128:131], v[204:207], v[108:111]
	v_mfma_f32_16x16x32_bf16 v[104:107], v[154:157], v[204:207], v[104:107]
	v_mfma_f32_16x16x32_bf16 v[100:103], v[128:131], v[212:215], v[100:103]
	v_mfma_f32_16x16x32_bf16 v[96:99], v[154:157], v[212:215], v[96:99]
	v_mfma_f32_16x16x32_bf16 v[124:127], v[132:135], v[192:195], v[124:127]
	v_mfma_f32_16x16x32_bf16 v[120:123], v[158:161], v[192:195], v[120:123]
	v_mfma_f32_16x16x32_bf16 v[116:119], v[132:135], v[200:203], v[116:119]
	v_mfma_f32_16x16x32_bf16 v[112:115], v[158:161], v[200:203], v[112:115]
	v_mfma_f32_16x16x32_bf16 v[108:111], v[132:135], v[208:211], v[108:111]
	v_mfma_f32_16x16x32_bf16 v[104:107], v[158:161], v[208:211], v[104:107]
	v_mfma_f32_16x16x32_bf16 v[100:103], v[132:135], v[216:219], v[100:103]
	v_mfma_f32_16x16x32_bf16 v[96:99], v[158:161], v[216:219], v[96:99]
	s_setprio 0
	s_setprio 1
	v_mfma_f32_16x16x32_bf16 v[60:63], v[162:165], v[184:187], v[60:63]
	v_mfma_f32_16x16x32_bf16 v[56:59], v[170:173], v[184:187], v[56:59]
	v_mfma_f32_16x16x32_bf16 v[52:55], v[162:165], v[196:199], v[52:55]
	v_mfma_f32_16x16x32_bf16 v[48:51], v[170:173], v[196:199], v[48:51]
	v_mfma_f32_16x16x32_bf16 v[44:47], v[162:165], v[204:207], v[44:47]
	v_mfma_f32_16x16x32_bf16 v[40:43], v[170:173], v[204:207], v[40:43]
	v_mfma_f32_16x16x32_bf16 v[36:39], v[162:165], v[212:215], v[36:39]
	v_mfma_f32_16x16x32_bf16 v[32:35], v[170:173], v[212:215], v[32:35]
	v_mfma_f32_16x16x32_bf16 v[60:63], v[166:169], v[192:195], v[60:63]
	v_mfma_f32_16x16x32_bf16 v[56:59], v[180:183], v[192:195], v[56:59]
	v_mfma_f32_16x16x32_bf16 v[52:55], v[166:169], v[200:203], v[52:55]
	v_mfma_f32_16x16x32_bf16 v[48:51], v[180:183], v[200:203], v[48:51]
	v_mfma_f32_16x16x32_bf16 v[44:47], v[166:169], v[208:211], v[44:47]
	v_mfma_f32_16x16x32_bf16 v[40:43], v[180:183], v[208:211], v[40:43]
	v_mfma_f32_16x16x32_bf16 v[36:39], v[166:169], v[216:219], v[36:39]
	v_mfma_f32_16x16x32_bf16 v[32:35], v[180:183], v[216:219], v[32:35]
	s_setprio 0
	s_barrier
	s_add_i32 s86, s72, s56
	s_mov_b32 m0, s86
	ds_read_b128 v[184:187], v177 offset:16384
	ds_read_b128 v[192:195], v177 offset:17408
	ds_read_b128 v[196:199], v177 offset:18432
	ds_read_b128 v[200:203], v177 offset:19456
	ds_read_b128 v[204:207], v177 offset:20480
	ds_read_b128 v[208:211], v177 offset:21504
	ds_read_b128 v[212:215], v177 offset:22528
	ds_read_b128 v[216:219], v177 offset:23552
	global_load_lds_dwordx4 v138, s[28:29]
	s_add_i32 m0, s86, 0x2000
	s_add_u32 s86, s28, 0x40000
	s_addc_u32 s87, s29, 0
	s_add_i32 s88, s73, s56
	global_load_lds_dwordx4 v142, s[28:29]
	s_mov_b32 m0, s88
	s_mov_b64 s[98:99], s[36:37]
	global_load_lds_dwordx4 v138, s[86:87]
	s_add_i32 m0, s88, 0x2000
	s_nop 0
	global_load_lds_dwordx4 v142, s[86:87]
	s_mov_b32 m0, s57
	s_nop 0
	global_load_lds_dwordx4 v136, s[36:37]
	s_mov_b32 m0, s60
	s_nop 0
	global_load_lds_dwordx4 v140, s[36:37]
	s_waitcnt vmcnt(8)
	s_waitcnt lgkmcnt(0)
	s_barrier
	s_setprio 1
	s_waitcnt lgkmcnt(0)
	v_mfma_f32_16x16x32_bf16 v[92:95], v[128:131], v[184:187], v[92:95]
	v_mfma_f32_16x16x32_bf16 v[88:91], v[154:157], v[184:187], v[88:91]
	v_mfma_f32_16x16x32_bf16 v[84:87], v[128:131], v[196:199], v[84:87]
	v_mfma_f32_16x16x32_bf16 v[80:83], v[154:157], v[196:199], v[80:83]
	v_mfma_f32_16x16x32_bf16 v[76:79], v[128:131], v[204:207], v[76:79]
	v_mfma_f32_16x16x32_bf16 v[72:75], v[154:157], v[204:207], v[72:75]
	v_mfma_f32_16x16x32_bf16 v[68:71], v[128:131], v[212:215], v[68:71]
	v_mfma_f32_16x16x32_bf16 v[64:67], v[154:157], v[212:215], v[64:67]
	v_mfma_f32_16x16x32_bf16 v[92:95], v[132:135], v[192:195], v[92:95]
	v_mfma_f32_16x16x32_bf16 v[88:91], v[158:161], v[192:195], v[88:91]
	v_mfma_f32_16x16x32_bf16 v[84:87], v[132:135], v[200:203], v[84:87]
	v_mfma_f32_16x16x32_bf16 v[80:83], v[158:161], v[200:203], v[80:83]
	v_mfma_f32_16x16x32_bf16 v[76:79], v[132:135], v[208:211], v[76:79]
	v_mfma_f32_16x16x32_bf16 v[72:75], v[158:161], v[208:211], v[72:75]
	v_mfma_f32_16x16x32_bf16 v[68:71], v[132:135], v[216:219], v[68:71]
	v_mfma_f32_16x16x32_bf16 v[64:67], v[158:161], v[216:219], v[64:67]
	s_setprio 0
	s_setprio 1
	v_mfma_f32_16x16x32_bf16 v[28:31], v[162:165], v[184:187], v[28:31]
	v_mfma_f32_16x16x32_bf16 v[24:27], v[170:173], v[184:187], v[24:27]
	v_mfma_f32_16x16x32_bf16 v[20:23], v[162:165], v[196:199], v[20:23]
	v_mfma_f32_16x16x32_bf16 v[16:19], v[170:173], v[196:199], v[16:19]
	v_mfma_f32_16x16x32_bf16 v[12:15], v[162:165], v[204:207], v[12:15]
	v_mfma_f32_16x16x32_bf16 v[8:11], v[170:173], v[204:207], v[8:11]
	v_mfma_f32_16x16x32_bf16 v[4:7], v[162:165], v[212:215], v[4:7]
	v_mfma_f32_16x16x32_bf16 v[0:3], v[170:173], v[212:215], v[0:3]
	v_mfma_f32_16x16x32_bf16 v[28:31], v[166:169], v[192:195], v[28:31]
	v_mfma_f32_16x16x32_bf16 v[24:27], v[180:183], v[192:195], v[24:27]
	v_mfma_f32_16x16x32_bf16 v[20:23], v[166:169], v[200:203], v[20:23]
	v_mfma_f32_16x16x32_bf16 v[16:19], v[180:183], v[200:203], v[16:19]
	v_mfma_f32_16x16x32_bf16 v[12:15], v[166:169], v[208:211], v[12:15]
	v_mfma_f32_16x16x32_bf16 v[8:11], v[180:183], v[208:211], v[8:11]
	v_mfma_f32_16x16x32_bf16 v[4:7], v[166:169], v[216:219], v[4:7]
	v_mfma_f32_16x16x32_bf16 v[0:3], v[180:183], v[216:219], v[0:3]
	s_setprio 0
	s_barrier
	s_add_i32 s86, 0, 0x18000
	v_add_u32_e32 v144, s86, v174
	s_add_i32 s87, 0, 0x1c000
	ds_read_b128 v[128:131], v144
	ds_read_b128 v[132:135], v144 offset:1024
	ds_read_b128 v[154:157], v144 offset:2048
	ds_read_b128 v[158:161], v144 offset:3072
	v_add_u32_e32 v144, s87, v174
	ds_read_b128 v[162:165], v144
	ds_read_b128 v[166:169], v144 offset:1024
	ds_read_b128 v[170:173], v144 offset:2048
	ds_read_b128 v[180:183], v144 offset:3072
	s_add_u32 s36, s36, 0x40000
	s_addc_u32 s37, s37, 0
	s_mov_b32 m0, s61
	ds_read_b128 v[184:187], v177 offset:32768
	ds_read_b128 v[192:195], v177 offset:33792
	ds_read_b128 v[196:199], v177 offset:34816
	ds_read_b128 v[200:203], v177 offset:35840
	ds_read_b128 v[204:207], v177 offset:36864
	ds_read_b128 v[208:211], v177 offset:37888
	ds_read_b128 v[212:215], v177 offset:38912
	ds_read_b128 v[216:219], v177 offset:39936
	global_load_lds_dwordx4 v136, s[36:37]
	s_mov_b32 m0, s62
	s_nop 0
	global_load_lds_dwordx4 v140, s[36:37]
	s_waitcnt vmcnt(8)
	s_waitcnt lgkmcnt(0)
	s_barrier
	s_setprio 1
	s_waitcnt lgkmcnt(0)
	v_mfma_f32_16x16x32_bf16 v[124:127], v[128:131], v[184:187], v[124:127]
	v_mfma_f32_16x16x32_bf16 v[120:123], v[154:157], v[184:187], v[120:123]
	v_mfma_f32_16x16x32_bf16 v[116:119], v[128:131], v[196:199], v[116:119]
	v_mfma_f32_16x16x32_bf16 v[112:115], v[154:157], v[196:199], v[112:115]
	v_mfma_f32_16x16x32_bf16 v[108:111], v[128:131], v[204:207], v[108:111]
	v_mfma_f32_16x16x32_bf16 v[104:107], v[154:157], v[204:207], v[104:107]
	v_mfma_f32_16x16x32_bf16 v[100:103], v[128:131], v[212:215], v[100:103]
	v_mfma_f32_16x16x32_bf16 v[96:99], v[154:157], v[212:215], v[96:99]
	v_mfma_f32_16x16x32_bf16 v[124:127], v[132:135], v[192:195], v[124:127]
	v_mfma_f32_16x16x32_bf16 v[120:123], v[158:161], v[192:195], v[120:123]
	v_mfma_f32_16x16x32_bf16 v[116:119], v[132:135], v[200:203], v[116:119]
	v_mfma_f32_16x16x32_bf16 v[112:115], v[158:161], v[200:203], v[112:115]
	v_mfma_f32_16x16x32_bf16 v[108:111], v[132:135], v[208:211], v[108:111]
	v_mfma_f32_16x16x32_bf16 v[104:107], v[158:161], v[208:211], v[104:107]
	v_mfma_f32_16x16x32_bf16 v[100:103], v[132:135], v[216:219], v[100:103]
	v_mfma_f32_16x16x32_bf16 v[96:99], v[158:161], v[216:219], v[96:99]
	s_setprio 0
	s_setprio 1
	v_mfma_f32_16x16x32_bf16 v[60:63], v[162:165], v[184:187], v[60:63]
	v_mfma_f32_16x16x32_bf16 v[56:59], v[170:173], v[184:187], v[56:59]
	v_mfma_f32_16x16x32_bf16 v[52:55], v[162:165], v[196:199], v[52:55]
	v_mfma_f32_16x16x32_bf16 v[48:51], v[170:173], v[196:199], v[48:51]
	v_mfma_f32_16x16x32_bf16 v[44:47], v[162:165], v[204:207], v[44:47]
	v_mfma_f32_16x16x32_bf16 v[40:43], v[170:173], v[204:207], v[40:43]
	v_mfma_f32_16x16x32_bf16 v[36:39], v[162:165], v[212:215], v[36:39]
	v_mfma_f32_16x16x32_bf16 v[32:35], v[170:173], v[212:215], v[32:35]
	v_mfma_f32_16x16x32_bf16 v[60:63], v[166:169], v[192:195], v[60:63]
	v_mfma_f32_16x16x32_bf16 v[56:59], v[180:183], v[192:195], v[56:59]
	v_mfma_f32_16x16x32_bf16 v[52:55], v[166:169], v[200:203], v[52:55]
	v_mfma_f32_16x16x32_bf16 v[48:51], v[180:183], v[200:203], v[48:51]
	v_mfma_f32_16x16x32_bf16 v[44:47], v[166:169], v[208:211], v[44:47]
	v_mfma_f32_16x16x32_bf16 v[40:43], v[180:183], v[208:211], v[40:43]
	v_mfma_f32_16x16x32_bf16 v[36:39], v[166:169], v[216:219], v[36:39]
	v_mfma_f32_16x16x32_bf16 v[32:35], v[180:183], v[216:219], v[32:35]
	s_setprio 0
	s_barrier
	s_add_i32 s36, s86, s56
	s_add_i32 m0, s36, 0xffffff80
	ds_read_b128 v[184:187], v177 offset:49152
	ds_read_b128 v[192:195], v177 offset:50176
	ds_read_b128 v[196:199], v177 offset:51200
	ds_read_b128 v[200:203], v177 offset:52224
	ds_read_b128 v[204:207], v177 offset:53248
	ds_read_b128 v[208:211], v177 offset:54272
	ds_read_b128 v[212:215], v177 offset:55296
	ds_read_b128 v[216:219], v177 offset:56320
	global_load_lds_dwordx4 v138, s[28:29] offset:128
	s_add_i32 m0, s36, 0x1f80
	s_add_i32 s36, s87, s56
	global_load_lds_dwordx4 v142, s[28:29] offset:128
	s_add_u32 s28, s28, 0x40080
	s_addc_u32 s29, s29, 0
	s_mov_b32 m0, s36
	s_nop 0
	global_load_lds_dwordx4 v138, s[28:29]
	s_add_i32 m0, s36, 0x2000
	s_nop 0
	global_load_lds_dwordx4 v142, s[28:29]
	s_add_i32 m0, s66, 0xffffff80
	s_nop 0
	global_load_lds_dwordx4 v136, s[98:99] offset:128
	s_add_i32 m0, s67, 0xffffff80
	s_nop 0
	global_load_lds_dwordx4 v140, s[98:99] offset:128
	s_waitcnt vmcnt(8)
	s_waitcnt lgkmcnt(0)
	s_barrier
	s_setprio 1
	s_waitcnt lgkmcnt(0)
	v_mfma_f32_16x16x32_bf16 v[92:95], v[128:131], v[184:187], v[92:95]
	v_mfma_f32_16x16x32_bf16 v[88:91], v[154:157], v[184:187], v[88:91]
	v_mfma_f32_16x16x32_bf16 v[84:87], v[128:131], v[196:199], v[84:87]
	v_mfma_f32_16x16x32_bf16 v[80:83], v[154:157], v[196:199], v[80:83]
	v_mfma_f32_16x16x32_bf16 v[76:79], v[128:131], v[204:207], v[76:79]
	v_mfma_f32_16x16x32_bf16 v[72:75], v[154:157], v[204:207], v[72:75]
	v_mfma_f32_16x16x32_bf16 v[68:71], v[128:131], v[212:215], v[68:71]
	v_mfma_f32_16x16x32_bf16 v[64:67], v[154:157], v[212:215], v[64:67]
	v_mfma_f32_16x16x32_bf16 v[92:95], v[132:135], v[192:195], v[92:95]
	v_mfma_f32_16x16x32_bf16 v[88:91], v[158:161], v[192:195], v[88:91]
	v_mfma_f32_16x16x32_bf16 v[84:87], v[132:135], v[200:203], v[84:87]
	v_mfma_f32_16x16x32_bf16 v[80:83], v[158:161], v[200:203], v[80:83]
	v_mfma_f32_16x16x32_bf16 v[76:79], v[132:135], v[208:211], v[76:79]
	v_mfma_f32_16x16x32_bf16 v[72:75], v[158:161], v[208:211], v[72:75]
	v_mfma_f32_16x16x32_bf16 v[68:71], v[132:135], v[216:219], v[68:71]
	v_mfma_f32_16x16x32_bf16 v[64:67], v[158:161], v[216:219], v[64:67]
	s_setprio 0
	s_setprio 1
	v_mfma_f32_16x16x32_bf16 v[28:31], v[162:165], v[184:187], v[28:31]
	v_mfma_f32_16x16x32_bf16 v[24:27], v[170:173], v[184:187], v[24:27]
	v_mfma_f32_16x16x32_bf16 v[20:23], v[162:165], v[196:199], v[20:23]
	v_mfma_f32_16x16x32_bf16 v[16:19], v[170:173], v[196:199], v[16:19]
	v_mfma_f32_16x16x32_bf16 v[12:15], v[162:165], v[204:207], v[12:15]
	v_mfma_f32_16x16x32_bf16 v[8:11], v[170:173], v[204:207], v[8:11]
	v_mfma_f32_16x16x32_bf16 v[4:7], v[162:165], v[212:215], v[4:7]
	v_mfma_f32_16x16x32_bf16 v[0:3], v[170:173], v[212:215], v[0:3]
	v_mfma_f32_16x16x32_bf16 v[28:31], v[166:169], v[192:195], v[28:31]
	v_mfma_f32_16x16x32_bf16 v[24:27], v[180:183], v[192:195], v[24:27]
	v_mfma_f32_16x16x32_bf16 v[20:23], v[166:169], v[200:203], v[20:23]
	v_mfma_f32_16x16x32_bf16 v[16:19], v[180:183], v[200:203], v[16:19]
	v_mfma_f32_16x16x32_bf16 v[12:15], v[166:169], v[208:211], v[12:15]
	v_mfma_f32_16x16x32_bf16 v[8:11], v[180:183], v[208:211], v[8:11]
	v_mfma_f32_16x16x32_bf16 v[4:7], v[166:169], v[216:219], v[4:7]
	v_mfma_f32_16x16x32_bf16 v[0:3], v[180:183], v[216:219], v[0:3]
	s_setprio 0
	s_barrier
	s_add_u32 s10, s10, 0x100
	s_addc_u32 s11, s11, 0
	s_add_u32 s79, s79, 0x100
	s_addc_u32 s84, s84, 0
	s_cmp_ge_i32 s85, s3
	s_mov_b32 s28, s85
	s_cbranch_scc0 .LBB0_282
	s_and_b64 vcc, exec, s[44:45]
	s_cbranch_vccz .LBB0_285

.LBB0_404:
	s_nop 0
	v_readlane_b32 s4, v236, 5
	s_cmp_lt_i32 s4, 3
	s_cselect_b64 s[20:21], -1, 0
	s_and_b64 s[0:1], s[0:1], s[20:21]
	s_andn2_b64 vcc, exec, s[0:1]
	v_readlane_b32 s5, v236, 6
	s_cbranch_vccnz .LBB0_481
	v_mov_b32_e32 v1, v191
	s_lshl_b32 s3, s2, 9
	v_readfirstlane_b32 s0, v1
	s_andn2_b32 s0, s0, 63
	s_add_i32 s0, s0, s3
	v_and_or_b32 v0, v1, 63, s0
	s_mov_b32 s1, 0x80000
	s_lshl_b32 s0, s30, 9
	v_cmp_gt_i32_e32 vcc, s1, v0
	s_and_saveexec_b64 s[4:5], vcc
	s_cbranch_execz .LBB0_408
	v_and_b32_e32 v10, 15, v1
	v_mov_b32_e32 v3, 0
	v_lshlrev_b32_e32 v2, 1, v10
	v_lshl_add_u64 v[4:5], s[26:27], 0, v[2:3]
	s_mov_b64 s[6:7], 0x1b000000
	v_ashrrev_i32_e32 v1, 31, v0
	v_lshl_add_u64 v[4:5], v[4:5], 0, s[6:7]
	v_lshl_add_u64 v[6:7], v[0:1], 2, s[26:27]
	s_mov_b64 s[6:7], 0x2800000
	s_ashr_i32 s1, s0, 31
	v_lshl_add_u64 v[6:7], v[6:7], 0, s[6:7]
	s_lshl_b64 s[6:7], s[0:1], 2
	s_mov_b64 s[10:11], 0
	s_movk_i32 s1, 0x1a00
	v_mov_b64_e32 v[8:9], s[14:15]
	v_lshlrev_b32_e32 v2, 1, v10
	s_movk_i32 s28, 0x7fff
	s_mov_b32 s29, 0x7ffff

.LBB0_1033:
	s_add_i32 s71, s36, 2
	s_add_u32 s37, s28, 0xe5fbf080
	s_addc_u32 s42, s29, -1
	s_cmp_lg_u32 s70, s36
	s_cselect_b32 s36, s37, 0
	s_cselect_b32 s72, s42, 0
	s_add_u32 s42, s10, s36
	s_addc_u32 s43, s11, s72
	s_add_i32 s73, 0, 0x10000
	s_add_u32 s36, s4, s36
	s_addc_u32 s37, s5, s72
	s_add_i32 s74, 0, 0x14000
	v_add_u32_e32 v160, s73, v146
	v_add_u32_e32 v176, s74, v146
	ds_read_b128 v[148:151], v160
	ds_read_b128 v[152:155], v160 offset:1024
	ds_read_b128 v[156:159], v160 offset:2048
	ds_read_b128 v[160:163], v160 offset:3072
	ds_read_b128 v[164:167], v176
	ds_read_b128 v[168:171], v176 offset:1024
	ds_read_b128 v[172:175], v176 offset:2048
	ds_read_b128 v[176:179], v176 offset:3072
	v_lshl_add_u64 v[188:189], v[138:139], 0, s[28:29]
	s_add_i32 m0, s64, 0xc000
	ds_read_b128 v[180:183], v147
	ds_read_b128 v[184:187], v147 offset:1024
	ds_read_b128 v[192:195], v147 offset:2048
	ds_read_b128 v[196:199], v147 offset:3072
	ds_read_b128 v[200:203], v147 offset:4096
	ds_read_b128 v[204:207], v147 offset:5120
	ds_read_b128 v[208:211], v147 offset:6144
	ds_read_b128 v[212:215], v147 offset:7168
	global_load_lds_dwordx4 v[188:189], off
	v_lshl_add_u64 v[188:189], v[140:141], 0, s[28:29]
	s_add_i32 m0, s64, 0xe000
	s_nop 0
	global_load_lds_dwordx4 v[188:189], off
	s_waitcnt vmcnt(8)
	s_waitcnt lgkmcnt(0)
	s_barrier
	s_setprio 1
	s_waitcnt lgkmcnt(0)
	v_mfma_f32_16x16x32_bf16 v[124:127], v[148:151], v[180:183], v[124:127]
	v_mfma_f32_16x16x32_bf16 v[120:123], v[156:159], v[180:183], v[120:123]
	v_mfma_f32_16x16x32_bf16 v[108:111], v[148:151], v[192:195], v[108:111]
	v_mfma_f32_16x16x32_bf16 v[104:107], v[156:159], v[192:195], v[104:107]
	v_mfma_f32_16x16x32_bf16 v[92:95], v[148:151], v[200:203], v[92:95]
	v_mfma_f32_16x16x32_bf16 v[88:91], v[156:159], v[200:203], v[88:91]
	v_mfma_f32_16x16x32_bf16 v[76:79], v[148:151], v[208:211], v[76:79]
	v_mfma_f32_16x16x32_bf16 v[72:75], v[156:159], v[208:211], v[72:75]
	v_mfma_f32_16x16x32_bf16 v[124:127], v[152:155], v[184:187], v[124:127]
	v_mfma_f32_16x16x32_bf16 v[120:123], v[160:163], v[184:187], v[120:123]
	v_mfma_f32_16x16x32_bf16 v[108:111], v[152:155], v[196:199], v[108:111]
	v_mfma_f32_16x16x32_bf16 v[104:107], v[160:163], v[196:199], v[104:107]
	v_mfma_f32_16x16x32_bf16 v[92:95], v[152:155], v[204:207], v[92:95]
	v_mfma_f32_16x16x32_bf16 v[88:91], v[160:163], v[204:207], v[88:91]
	v_mfma_f32_16x16x32_bf16 v[76:79], v[152:155], v[212:215], v[76:79]
	v_mfma_f32_16x16x32_bf16 v[72:75], v[160:163], v[212:215], v[72:75]
	s_setprio 0
	s_setprio 1
	v_mfma_f32_16x16x32_bf16 v[116:119], v[164:167], v[180:183], v[116:119]
	v_mfma_f32_16x16x32_bf16 v[112:115], v[172:175], v[180:183], v[112:115]
	v_mfma_f32_16x16x32_bf16 v[100:103], v[164:167], v[192:195], v[100:103]
	v_mfma_f32_16x16x32_bf16 v[96:99], v[172:175], v[192:195], v[96:99]
	v_mfma_f32_16x16x32_bf16 v[84:87], v[164:167], v[200:203], v[84:87]
	v_mfma_f32_16x16x32_bf16 v[80:83], v[172:175], v[200:203], v[80:83]
	v_mfma_f32_16x16x32_bf16 v[68:71], v[164:167], v[208:211], v[68:71]
	v_mfma_f32_16x16x32_bf16 v[64:67], v[172:175], v[208:211], v[64:67]
	v_mfma_f32_16x16x32_bf16 v[116:119], v[168:171], v[184:187], v[116:119]
	v_mfma_f32_16x16x32_bf16 v[112:115], v[176:179], v[184:187], v[112:115]
	v_mfma_f32_16x16x32_bf16 v[100:103], v[168:171], v[196:199], v[100:103]
	v_mfma_f32_16x16x32_bf16 v[96:99], v[176:179], v[196:199], v[96:99]
	v_mfma_f32_16x16x32_bf16 v[84:87], v[168:171], v[204:207], v[84:87]
	v_mfma_f32_16x16x32_bf16 v[80:83], v[176:179], v[204:207], v[80:83]
	v_mfma_f32_16x16x32_bf16 v[68:71], v[168:171], v[212:215], v[68:71]
	v_mfma_f32_16x16x32_bf16 v[64:67], v[176:179], v[212:215], v[64:67]
	s_setprio 0
	s_barrier
	s_add_i32 s72, s73, s63
	s_mov_b32 m0, s72
	ds_read_b128 v[180:183], v147 offset:16384
	ds_read_b128 v[184:187], v147 offset:17408
	ds_read_b128 v[192:195], v147 offset:18432
	ds_read_b128 v[196:199], v147 offset:19456
	ds_read_b128 v[200:203], v147 offset:20480
	ds_read_b128 v[204:207], v147 offset:21504
	ds_read_b128 v[208:211], v147 offset:22528
	ds_read_b128 v[212:215], v147 offset:23552
	global_load_lds_dwordx4 v130, s[36:37]
	s_add_i32 m0, s72, 0x2000
	s_add_u32 s72, s36, 0x40000
	s_addc_u32 s73, s37, 0
	s_add_i32 s74, s74, s63
	global_load_lds_dwordx4 v136, s[36:37]
	s_mov_b32 m0, s74
	s_mov_b64 s[98:99], s[42:43]
	global_load_lds_dwordx4 v130, s[72:73]
	s_add_i32 m0, s74, 0x2000
	s_nop 0
	global_load_lds_dwordx4 v136, s[72:73]
	s_mov_b32 m0, s64
	s_nop 0
	global_load_lds_dwordx4 v132, s[42:43]
	s_mov_b32 m0, s65
	s_nop 0
	global_load_lds_dwordx4 v134, s[42:43]
	s_waitcnt vmcnt(8)
	s_waitcnt lgkmcnt(0)
	s_barrier
	s_setprio 1
	s_waitcnt lgkmcnt(0)
	v_mfma_f32_16x16x32_bf16 v[60:63], v[148:151], v[180:183], v[60:63]
	v_mfma_f32_16x16x32_bf16 v[56:59], v[156:159], v[180:183], v[56:59]
	v_mfma_f32_16x16x32_bf16 v[44:47], v[148:151], v[192:195], v[44:47]
	v_mfma_f32_16x16x32_bf16 v[40:43], v[156:159], v[192:195], v[40:43]
	v_mfma_f32_16x16x32_bf16 v[28:31], v[148:151], v[200:203], v[28:31]
	v_mfma_f32_16x16x32_bf16 v[24:27], v[156:159], v[200:203], v[24:27]
	v_mfma_f32_16x16x32_bf16 v[12:15], v[148:151], v[208:211], v[12:15]
	v_mfma_f32_16x16x32_bf16 v[8:11], v[156:159], v[208:211], v[8:11]
	v_mfma_f32_16x16x32_bf16 v[60:63], v[152:155], v[184:187], v[60:63]
	v_mfma_f32_16x16x32_bf16 v[56:59], v[160:163], v[184:187], v[56:59]
	v_mfma_f32_16x16x32_bf16 v[44:47], v[152:155], v[196:199], v[44:47]
	v_mfma_f32_16x16x32_bf16 v[40:43], v[160:163], v[196:199], v[40:43]
	v_mfma_f32_16x16x32_bf16 v[28:31], v[152:155], v[204:207], v[28:31]
	v_mfma_f32_16x16x32_bf16 v[24:27], v[160:163], v[204:207], v[24:27]
	v_mfma_f32_16x16x32_bf16 v[12:15], v[152:155], v[212:215], v[12:15]
	v_mfma_f32_16x16x32_bf16 v[8:11], v[160:163], v[212:215], v[8:11]
	s_setprio 0
	s_setprio 1
	v_mfma_f32_16x16x32_bf16 v[52:55], v[164:167], v[180:183], v[52:55]
	v_mfma_f32_16x16x32_bf16 v[48:51], v[172:175], v[180:183], v[48:51]
	v_mfma_f32_16x16x32_bf16 v[36:39], v[164:167], v[192:195], v[36:39]
	v_mfma_f32_16x16x32_bf16 v[32:35], v[172:175], v[192:195], v[32:35]
	v_mfma_f32_16x16x32_bf16 v[20:23], v[164:167], v[200:203], v[20:23]
	v_mfma_f32_16x16x32_bf16 v[16:19], v[172:175], v[200:203], v[16:19]
	v_mfma_f32_16x16x32_bf16 v[4:7], v[164:167], v[208:211], v[4:7]
	v_mfma_f32_16x16x32_bf16 v[0:3], v[172:175], v[208:211], v[0:3]
	v_mfma_f32_16x16x32_bf16 v[52:55], v[168:171], v[184:187], v[52:55]
	v_mfma_f32_16x16x32_bf16 v[48:51], v[176:179], v[184:187], v[48:51]
	v_mfma_f32_16x16x32_bf16 v[36:39], v[168:171], v[196:199], v[36:39]
	v_mfma_f32_16x16x32_bf16 v[32:35], v[176:179], v[196:199], v[32:35]
	v_mfma_f32_16x16x32_bf16 v[20:23], v[168:171], v[204:207], v[20:23]
	v_mfma_f32_16x16x32_bf16 v[16:19], v[176:179], v[204:207], v[16:19]
	v_mfma_f32_16x16x32_bf16 v[4:7], v[168:171], v[212:215], v[4:7]
	v_mfma_f32_16x16x32_bf16 v[0:3], v[176:179], v[212:215], v[0:3]
	s_setprio 0
	s_barrier
	s_add_i32 s72, 0, 0x18000
	s_add_i32 s73, 0, 0x1c000
	v_add_u32_e32 v160, s72, v146
	v_add_u32_e32 v176, s73, v146
	ds_read_b128 v[148:151], v160
	ds_read_b128 v[152:155], v160 offset:1024
	ds_read_b128 v[156:159], v160 offset:2048
	ds_read_b128 v[160:163], v160 offset:3072
	ds_read_b128 v[164:167], v176
	ds_read_b128 v[168:171], v176 offset:1024
	ds_read_b128 v[172:175], v176 offset:2048
	ds_read_b128 v[176:179], v176 offset:3072
	s_add_u32 s42, s42, 0x40000
	s_addc_u32 s43, s43, 0
	s_mov_b32 m0, s66
	ds_read_b128 v[180:183], v147 offset:32768
	ds_read_b128 v[184:187], v147 offset:33792
	ds_read_b128 v[192:195], v147 offset:34816
	ds_read_b128 v[196:199], v147 offset:35840
	ds_read_b128 v[200:203], v147 offset:36864
	ds_read_b128 v[204:207], v147 offset:37888
	ds_read_b128 v[208:211], v147 offset:38912
	ds_read_b128 v[212:215], v147 offset:39936
	global_load_lds_dwordx4 v132, s[42:43]
	s_mov_b32 m0, s67
	s_nop 0
	global_load_lds_dwordx4 v134, s[42:43]
	s_waitcnt vmcnt(8)
	s_waitcnt lgkmcnt(0)
	s_barrier
	s_setprio 1
	s_waitcnt lgkmcnt(0)
	v_mfma_f32_16x16x32_bf16 v[124:127], v[148:151], v[180:183], v[124:127]
	v_mfma_f32_16x16x32_bf16 v[120:123], v[156:159], v[180:183], v[120:123]
	v_mfma_f32_16x16x32_bf16 v[108:111], v[148:151], v[192:195], v[108:111]
	v_mfma_f32_16x16x32_bf16 v[104:107], v[156:159], v[192:195], v[104:107]
	v_mfma_f32_16x16x32_bf16 v[92:95], v[148:151], v[200:203], v[92:95]
	v_mfma_f32_16x16x32_bf16 v[88:91], v[156:159], v[200:203], v[88:91]
	v_mfma_f32_16x16x32_bf16 v[76:79], v[148:151], v[208:211], v[76:79]
	v_mfma_f32_16x16x32_bf16 v[72:75], v[156:159], v[208:211], v[72:75]
	v_mfma_f32_16x16x32_bf16 v[124:127], v[152:155], v[184:187], v[124:127]
	v_mfma_f32_16x16x32_bf16 v[120:123], v[160:163], v[184:187], v[120:123]
	v_mfma_f32_16x16x32_bf16 v[108:111], v[152:155], v[196:199], v[108:111]
	v_mfma_f32_16x16x32_bf16 v[104:107], v[160:163], v[196:199], v[104:107]
	v_mfma_f32_16x16x32_bf16 v[92:95], v[152:155], v[204:207], v[92:95]
	v_mfma_f32_16x16x32_bf16 v[88:91], v[160:163], v[204:207], v[88:91]
	v_mfma_f32_16x16x32_bf16 v[76:79], v[152:155], v[212:215], v[76:79]
	v_mfma_f32_16x16x32_bf16 v[72:75], v[160:163], v[212:215], v[72:75]
	s_setprio 0
	s_setprio 1
	v_mfma_f32_16x16x32_bf16 v[116:119], v[164:167], v[180:183], v[116:119]
	v_mfma_f32_16x16x32_bf16 v[112:115], v[172:175], v[180:183], v[112:115]
	v_mfma_f32_16x16x32_bf16 v[100:103], v[164:167], v[192:195], v[100:103]
	v_mfma_f32_16x16x32_bf16 v[96:99], v[172:175], v[192:195], v[96:99]
	v_mfma_f32_16x16x32_bf16 v[84:87], v[164:167], v[200:203], v[84:87]
	v_mfma_f32_16x16x32_bf16 v[80:83], v[172:175], v[200:203], v[80:83]
	v_mfma_f32_16x16x32_bf16 v[68:71], v[164:167], v[208:211], v[68:71]
	v_mfma_f32_16x16x32_bf16 v[64:67], v[172:175], v[208:211], v[64:67]
	v_mfma_f32_16x16x32_bf16 v[116:119], v[168:171], v[184:187], v[116:119]
	v_mfma_f32_16x16x32_bf16 v[112:115], v[176:179], v[184:187], v[112:115]
	v_mfma_f32_16x16x32_bf16 v[100:103], v[168:171], v[196:199], v[100:103]
	v_mfma_f32_16x16x32_bf16 v[96:99], v[176:179], v[196:199], v[96:99]
	v_mfma_f32_16x16x32_bf16 v[84:87], v[168:171], v[204:207], v[84:87]
	v_mfma_f32_16x16x32_bf16 v[80:83], v[176:179], v[204:207], v[80:83]
	v_mfma_f32_16x16x32_bf16 v[68:71], v[168:171], v[212:215], v[68:71]
	v_mfma_f32_16x16x32_bf16 v[64:67], v[176:179], v[212:215], v[64:67]
	s_setprio 0
	s_barrier
	s_add_i32 s42, s72, s63
	s_add_i32 m0, s42, 0xffffff80
	ds_read_b128 v[180:183], v147 offset:49152
	ds_read_b128 v[184:187], v147 offset:50176
	ds_read_b128 v[192:195], v147 offset:51200
	ds_read_b128 v[196:199], v147 offset:52224
	ds_read_b128 v[200:203], v147 offset:53248
	ds_read_b128 v[204:207], v147 offset:54272
	ds_read_b128 v[208:211], v147 offset:55296
	ds_read_b128 v[212:215], v147 offset:56320
	global_load_lds_dwordx4 v130, s[36:37] offset:128
	s_add_i32 m0, s42, 0x1f80
	s_add_i32 s42, s73, s63
	global_load_lds_dwordx4 v136, s[36:37] offset:128
	s_add_u32 s36, s36, 0x40080
	s_addc_u32 s37, s37, 0
	s_mov_b32 m0, s42
	s_nop 0
	global_load_lds_dwordx4 v130, s[36:37]
	s_add_i32 m0, s42, 0x2000
	s_nop 0
	global_load_lds_dwordx4 v136, s[36:37]
	s_add_i32 m0, s68, 0xffffff80
	s_nop 0
	global_load_lds_dwordx4 v132, s[98:99] offset:128
	s_add_i32 m0, s69, 0xffffff80
	s_nop 0
	global_load_lds_dwordx4 v134, s[98:99] offset:128
	s_waitcnt vmcnt(8)
	s_waitcnt lgkmcnt(0)
	s_barrier
	s_setprio 1
	s_waitcnt lgkmcnt(0)
	v_mfma_f32_16x16x32_bf16 v[60:63], v[148:151], v[180:183], v[60:63]
	v_mfma_f32_16x16x32_bf16 v[56:59], v[156:159], v[180:183], v[56:59]
	v_mfma_f32_16x16x32_bf16 v[44:47], v[148:151], v[192:195], v[44:47]
	v_mfma_f32_16x16x32_bf16 v[40:43], v[156:159], v[192:195], v[40:43]
	v_mfma_f32_16x16x32_bf16 v[28:31], v[148:151], v[200:203], v[28:31]
	v_mfma_f32_16x16x32_bf16 v[24:27], v[156:159], v[200:203], v[24:27]
	v_mfma_f32_16x16x32_bf16 v[12:15], v[148:151], v[208:211], v[12:15]
	v_mfma_f32_16x16x32_bf16 v[8:11], v[156:159], v[208:211], v[8:11]
	v_mfma_f32_16x16x32_bf16 v[60:63], v[152:155], v[184:187], v[60:63]
	v_mfma_f32_16x16x32_bf16 v[56:59], v[160:163], v[184:187], v[56:59]
	v_mfma_f32_16x16x32_bf16 v[44:47], v[152:155], v[196:199], v[44:47]
	v_mfma_f32_16x16x32_bf16 v[40:43], v[160:163], v[196:199], v[40:43]
	v_mfma_f32_16x16x32_bf16 v[28:31], v[152:155], v[204:207], v[28:31]
	v_mfma_f32_16x16x32_bf16 v[24:27], v[160:163], v[204:207], v[24:27]
	v_mfma_f32_16x16x32_bf16 v[12:15], v[152:155], v[212:215], v[12:15]
	v_mfma_f32_16x16x32_bf16 v[8:11], v[160:163], v[212:215], v[8:11]
	s_setprio 0
	s_setprio 1
	v_mfma_f32_16x16x32_bf16 v[52:55], v[164:167], v[180:183], v[52:55]
	v_mfma_f32_16x16x32_bf16 v[48:51], v[172:175], v[180:183], v[48:51]
	v_mfma_f32_16x16x32_bf16 v[36:39], v[164:167], v[192:195], v[36:39]
	v_mfma_f32_16x16x32_bf16 v[32:35], v[172:175], v[192:195], v[32:35]
	v_mfma_f32_16x16x32_bf16 v[20:23], v[164:167], v[200:203], v[20:23]
	v_mfma_f32_16x16x32_bf16 v[16:19], v[172:175], v[200:203], v[16:19]
	v_mfma_f32_16x16x32_bf16 v[4:7], v[164:167], v[208:211], v[4:7]
	v_mfma_f32_16x16x32_bf16 v[0:3], v[172:175], v[208:211], v[0:3]
	v_mfma_f32_16x16x32_bf16 v[52:55], v[168:171], v[184:187], v[52:55]
	v_mfma_f32_16x16x32_bf16 v[48:51], v[176:179], v[184:187], v[48:51]
	v_mfma_f32_16x16x32_bf16 v[36:39], v[168:171], v[196:199], v[36:39]
	v_mfma_f32_16x16x32_bf16 v[32:35], v[176:179], v[196:199], v[32:35]
	v_mfma_f32_16x16x32_bf16 v[20:23], v[168:171], v[204:207], v[20:23]
	v_mfma_f32_16x16x32_bf16 v[16:19], v[176:179], v[204:207], v[16:19]
	v_mfma_f32_16x16x32_bf16 v[4:7], v[168:171], v[212:215], v[4:7]
	v_mfma_f32_16x16x32_bf16 v[0:3], v[176:179], v[212:215], v[0:3]
	s_setprio 0
	s_barrier
	s_add_u32 s28, s28, 0x100
	s_addc_u32 s29, s29, 0
	s_cmp_ge_i32 s71, s62
	s_mov_b32 s36, s71
	s_cbranch_scc0 .LBB0_1033
	s_cmpk_lt_u32 s60, 0x100
	s_cbranch_scc0 .LBB0_1036

.LBB0_1117:
	ds_read_b128 v[148:151], v145
	ds_read_b128 v[152:155], v145 offset:1024
	ds_read_b128 v[156:159], v145 offset:2048
	ds_read_b128 v[160:163], v145 offset:3072
	ds_read_b128 v[164:167], v146
	ds_read_b128 v[168:171], v146 offset:1024
	ds_read_b128 v[172:175], v146 offset:2048
	ds_read_b128 v[176:179], v146 offset:3072
	s_add_i32 s68, s36, 2
	s_add_u32 s28, s10, 0x100
	s_addc_u32 s29, s11, 0
	s_cmp_eq_u32 s59, s36
	s_cselect_b32 s36, s42, s66
	s_cselect_b32 s45, s1, s29
	s_cselect_b32 s44, s0, s28
	s_cselect_b32 s37, s43, s67
	v_lshl_add_u64 v[188:189], s[10:11], 0, v[136:137]
	s_add_i32 m0, s50, 0xc000
	ds_read_b128 v[180:183], v147
	ds_read_b128 v[184:187], v147 offset:1024
	ds_read_b128 v[192:195], v147 offset:2048
	ds_read_b128 v[196:199], v147 offset:3072
	ds_read_b128 v[200:203], v147 offset:4096
	ds_read_b128 v[204:207], v147 offset:5120
	ds_read_b128 v[208:211], v147 offset:6144
	ds_read_b128 v[212:215], v147 offset:7168
	global_load_lds_dwordx4 v[188:189], off
	v_lshl_add_u64 v[188:189], s[10:11], 0, v[138:139]
	s_add_i32 m0, s50, 0xe000
	s_nop 0
	global_load_lds_dwordx4 v[188:189], off
	s_waitcnt vmcnt(8)
	s_waitcnt lgkmcnt(0)
	s_barrier
	s_setprio 1
	s_waitcnt lgkmcnt(0)
	v_mfma_f32_16x16x32_bf16 v[124:127], v[148:151], v[180:183], v[124:127]
	v_mfma_f32_16x16x32_bf16 v[120:123], v[156:159], v[180:183], v[120:123]
	v_mfma_f32_16x16x32_bf16 v[116:119], v[148:151], v[192:195], v[116:119]
	v_mfma_f32_16x16x32_bf16 v[112:115], v[156:159], v[192:195], v[112:115]
	v_mfma_f32_16x16x32_bf16 v[108:111], v[148:151], v[200:203], v[108:111]
	v_mfma_f32_16x16x32_bf16 v[104:107], v[156:159], v[200:203], v[104:107]
	v_mfma_f32_16x16x32_bf16 v[100:103], v[148:151], v[208:211], v[100:103]
	v_mfma_f32_16x16x32_bf16 v[96:99], v[156:159], v[208:211], v[96:99]
	v_mfma_f32_16x16x32_bf16 v[124:127], v[152:155], v[184:187], v[124:127]
	v_mfma_f32_16x16x32_bf16 v[120:123], v[160:163], v[184:187], v[120:123]
	v_mfma_f32_16x16x32_bf16 v[116:119], v[152:155], v[196:199], v[116:119]
	v_mfma_f32_16x16x32_bf16 v[112:115], v[160:163], v[196:199], v[112:115]
	v_mfma_f32_16x16x32_bf16 v[108:111], v[152:155], v[204:207], v[108:111]
	v_mfma_f32_16x16x32_bf16 v[104:107], v[160:163], v[204:207], v[104:107]
	v_mfma_f32_16x16x32_bf16 v[100:103], v[152:155], v[212:215], v[100:103]
	v_mfma_f32_16x16x32_bf16 v[96:99], v[160:163], v[212:215], v[96:99]
	s_setprio 0
	s_setprio 1
	v_mfma_f32_16x16x32_bf16 v[60:63], v[164:167], v[180:183], v[60:63]
	v_mfma_f32_16x16x32_bf16 v[56:59], v[172:175], v[180:183], v[56:59]
	v_mfma_f32_16x16x32_bf16 v[52:55], v[164:167], v[192:195], v[52:55]
	v_mfma_f32_16x16x32_bf16 v[48:51], v[172:175], v[192:195], v[48:51]
	v_mfma_f32_16x16x32_bf16 v[44:47], v[164:167], v[200:203], v[44:47]
	v_mfma_f32_16x16x32_bf16 v[40:43], v[172:175], v[200:203], v[40:43]
	v_mfma_f32_16x16x32_bf16 v[36:39], v[164:167], v[208:211], v[36:39]
	v_mfma_f32_16x16x32_bf16 v[32:35], v[172:175], v[208:211], v[32:35]
	v_mfma_f32_16x16x32_bf16 v[60:63], v[168:171], v[184:187], v[60:63]
	v_mfma_f32_16x16x32_bf16 v[56:59], v[176:179], v[184:187], v[56:59]
	v_mfma_f32_16x16x32_bf16 v[52:55], v[168:171], v[196:199], v[52:55]
	v_mfma_f32_16x16x32_bf16 v[48:51], v[176:179], v[196:199], v[48:51]
	v_mfma_f32_16x16x32_bf16 v[44:47], v[168:171], v[204:207], v[44:47]
	v_mfma_f32_16x16x32_bf16 v[40:43], v[176:179], v[204:207], v[40:43]
	v_mfma_f32_16x16x32_bf16 v[36:39], v[168:171], v[212:215], v[36:39]
	v_mfma_f32_16x16x32_bf16 v[32:35], v[176:179], v[212:215], v[32:35]
	s_setprio 0
	s_barrier
	s_add_i32 s10, s62, s49
	s_mov_b32 m0, s10
	ds_read_b128 v[180:183], v147 offset:16384
	ds_read_b128 v[184:187], v147 offset:17408
	ds_read_b128 v[192:195], v147 offset:18432
	ds_read_b128 v[196:199], v147 offset:19456
	ds_read_b128 v[200:203], v147 offset:20480
	ds_read_b128 v[204:207], v147 offset:21504
	ds_read_b128 v[208:211], v147 offset:22528
	ds_read_b128 v[212:215], v147 offset:23552
	global_load_lds_dwordx4 v130, s[36:37]
	s_add_i32 m0, s10, 0x2000
	s_add_u32 s10, s36, 0xb0000
	s_addc_u32 s11, s37, 0
	s_add_i32 s69, s63, s49
	global_load_lds_dwordx4 v134, s[36:37]
	s_mov_b32 m0, s69
	s_nop 0
	global_load_lds_dwordx4 v130, s[10:11]
	s_add_i32 m0, s69, 0x2000
	s_nop 0
	global_load_lds_dwordx4 v134, s[10:11]
	s_mov_b32 m0, s50
	s_nop 0
	global_load_lds_dwordx4 v128, s[44:45]
	s_mov_b32 m0, s51
	s_nop 0
	global_load_lds_dwordx4 v132, s[44:45]
	s_waitcnt vmcnt(8)
	s_waitcnt lgkmcnt(0)
	s_barrier
	s_setprio 1
	s_waitcnt lgkmcnt(0)
	v_mfma_f32_16x16x32_bf16 v[92:95], v[148:151], v[180:183], v[92:95]
	v_mfma_f32_16x16x32_bf16 v[88:91], v[156:159], v[180:183], v[88:91]
	v_mfma_f32_16x16x32_bf16 v[84:87], v[148:151], v[192:195], v[84:87]
	v_mfma_f32_16x16x32_bf16 v[80:83], v[156:159], v[192:195], v[80:83]
	v_mfma_f32_16x16x32_bf16 v[76:79], v[148:151], v[200:203], v[76:79]
	v_mfma_f32_16x16x32_bf16 v[72:75], v[156:159], v[200:203], v[72:75]
	v_mfma_f32_16x16x32_bf16 v[68:71], v[148:151], v[208:211], v[68:71]
	v_mfma_f32_16x16x32_bf16 v[64:67], v[156:159], v[208:211], v[64:67]
	v_mfma_f32_16x16x32_bf16 v[92:95], v[152:155], v[184:187], v[92:95]
	v_mfma_f32_16x16x32_bf16 v[88:91], v[160:163], v[184:187], v[88:91]
	v_mfma_f32_16x16x32_bf16 v[84:87], v[152:155], v[196:199], v[84:87]
	v_mfma_f32_16x16x32_bf16 v[80:83], v[160:163], v[196:199], v[80:83]
	v_mfma_f32_16x16x32_bf16 v[76:79], v[152:155], v[204:207], v[76:79]
	v_mfma_f32_16x16x32_bf16 v[72:75], v[160:163], v[204:207], v[72:75]
	v_mfma_f32_16x16x32_bf16 v[68:71], v[152:155], v[212:215], v[68:71]
	v_mfma_f32_16x16x32_bf16 v[64:67], v[160:163], v[212:215], v[64:67]
	s_setprio 0
	s_setprio 1
	v_mfma_f32_16x16x32_bf16 v[28:31], v[164:167], v[180:183], v[28:31]
	v_mfma_f32_16x16x32_bf16 v[24:27], v[172:175], v[180:183], v[24:27]
	v_mfma_f32_16x16x32_bf16 v[20:23], v[164:167], v[192:195], v[20:23]
	v_mfma_f32_16x16x32_bf16 v[16:19], v[172:175], v[192:195], v[16:19]
	v_mfma_f32_16x16x32_bf16 v[12:15], v[164:167], v[200:203], v[12:15]
	v_mfma_f32_16x16x32_bf16 v[8:11], v[172:175], v[200:203], v[8:11]
	v_mfma_f32_16x16x32_bf16 v[4:7], v[164:167], v[208:211], v[4:7]
	v_mfma_f32_16x16x32_bf16 v[0:3], v[172:175], v[208:211], v[0:3]
	v_mfma_f32_16x16x32_bf16 v[28:31], v[168:171], v[184:187], v[28:31]
	v_mfma_f32_16x16x32_bf16 v[24:27], v[176:179], v[184:187], v[24:27]
	v_mfma_f32_16x16x32_bf16 v[20:23], v[168:171], v[196:199], v[20:23]
	v_mfma_f32_16x16x32_bf16 v[16:19], v[176:179], v[196:199], v[16:19]
	v_mfma_f32_16x16x32_bf16 v[12:15], v[168:171], v[204:207], v[12:15]
	v_mfma_f32_16x16x32_bf16 v[8:11], v[176:179], v[204:207], v[8:11]
	v_mfma_f32_16x16x32_bf16 v[4:7], v[168:171], v[212:215], v[4:7]
	v_mfma_f32_16x16x32_bf16 v[0:3], v[176:179], v[212:215], v[0:3]
	s_setprio 0
	s_barrier
	s_add_i32 s69, 0, 0x18000
	s_add_i32 s70, 0, 0x1c000
	v_add_u32_e32 v160, s69, v144
	v_add_u32_e32 v176, s70, v144
	ds_read_b128 v[148:151], v160
	ds_read_b128 v[152:155], v160 offset:1024
	ds_read_b128 v[156:159], v160 offset:2048
	ds_read_b128 v[160:163], v160 offset:3072
	ds_read_b128 v[164:167], v176
	ds_read_b128 v[168:171], v176 offset:1024
	ds_read_b128 v[172:175], v176 offset:2048
	ds_read_b128 v[176:179], v176 offset:3072
	s_add_u32 s10, s44, 0xb0000
	s_addc_u32 s11, s45, 0
	s_mov_b32 m0, s52
	ds_read_b128 v[180:183], v147 offset:32768
	ds_read_b128 v[184:187], v147 offset:33792
	ds_read_b128 v[192:195], v147 offset:34816
	ds_read_b128 v[196:199], v147 offset:35840
	ds_read_b128 v[200:203], v147 offset:36864
	ds_read_b128 v[204:207], v147 offset:37888
	ds_read_b128 v[208:211], v147 offset:38912
	ds_read_b128 v[212:215], v147 offset:39936
	global_load_lds_dwordx4 v128, s[10:11]
	s_mov_b32 m0, s53
	s_nop 0
	global_load_lds_dwordx4 v132, s[10:11]
	s_waitcnt vmcnt(8)
	s_waitcnt lgkmcnt(0)
	s_barrier
	s_setprio 1
	s_waitcnt lgkmcnt(0)
	v_mfma_f32_16x16x32_bf16 v[124:127], v[148:151], v[180:183], v[124:127]
	v_mfma_f32_16x16x32_bf16 v[120:123], v[156:159], v[180:183], v[120:123]
	v_mfma_f32_16x16x32_bf16 v[116:119], v[148:151], v[192:195], v[116:119]
	v_mfma_f32_16x16x32_bf16 v[112:115], v[156:159], v[192:195], v[112:115]
	v_mfma_f32_16x16x32_bf16 v[108:111], v[148:151], v[200:203], v[108:111]
	v_mfma_f32_16x16x32_bf16 v[104:107], v[156:159], v[200:203], v[104:107]
	v_mfma_f32_16x16x32_bf16 v[100:103], v[148:151], v[208:211], v[100:103]
	v_mfma_f32_16x16x32_bf16 v[96:99], v[156:159], v[208:211], v[96:99]
	v_mfma_f32_16x16x32_bf16 v[124:127], v[152:155], v[184:187], v[124:127]
	v_mfma_f32_16x16x32_bf16 v[120:123], v[160:163], v[184:187], v[120:123]
	v_mfma_f32_16x16x32_bf16 v[116:119], v[152:155], v[196:199], v[116:119]
	v_mfma_f32_16x16x32_bf16 v[112:115], v[160:163], v[196:199], v[112:115]
	v_mfma_f32_16x16x32_bf16 v[108:111], v[152:155], v[204:207], v[108:111]
	v_mfma_f32_16x16x32_bf16 v[104:107], v[160:163], v[204:207], v[104:107]
	v_mfma_f32_16x16x32_bf16 v[100:103], v[152:155], v[212:215], v[100:103]
	v_mfma_f32_16x16x32_bf16 v[96:99], v[160:163], v[212:215], v[96:99]
	s_setprio 0
	s_setprio 1
	v_mfma_f32_16x16x32_bf16 v[60:63], v[164:167], v[180:183], v[60:63]
	v_mfma_f32_16x16x32_bf16 v[56:59], v[172:175], v[180:183], v[56:59]
	v_mfma_f32_16x16x32_bf16 v[52:55], v[164:167], v[192:195], v[52:55]
	v_mfma_f32_16x16x32_bf16 v[48:51], v[172:175], v[192:195], v[48:51]
	v_mfma_f32_16x16x32_bf16 v[44:47], v[164:167], v[200:203], v[44:47]
	v_mfma_f32_16x16x32_bf16 v[40:43], v[172:175], v[200:203], v[40:43]
	v_mfma_f32_16x16x32_bf16 v[36:39], v[164:167], v[208:211], v[36:39]
	v_mfma_f32_16x16x32_bf16 v[32:35], v[172:175], v[208:211], v[32:35]
	v_mfma_f32_16x16x32_bf16 v[60:63], v[168:171], v[184:187], v[60:63]
	v_mfma_f32_16x16x32_bf16 v[56:59], v[176:179], v[184:187], v[56:59]
	v_mfma_f32_16x16x32_bf16 v[52:55], v[168:171], v[196:199], v[52:55]
	v_mfma_f32_16x16x32_bf16 v[48:51], v[176:179], v[196:199], v[48:51]
	v_mfma_f32_16x16x32_bf16 v[44:47], v[168:171], v[204:207], v[44:47]
	v_mfma_f32_16x16x32_bf16 v[40:43], v[176:179], v[204:207], v[40:43]
	v_mfma_f32_16x16x32_bf16 v[36:39], v[168:171], v[212:215], v[36:39]
	v_mfma_f32_16x16x32_bf16 v[32:35], v[176:179], v[212:215], v[32:35]
	s_setprio 0
	s_barrier
	s_add_i32 s10, s69, s49
	s_add_i32 m0, s10, 0xffffff80
	ds_read_b128 v[180:183], v147 offset:49152
	ds_read_b128 v[184:187], v147 offset:50176
	ds_read_b128 v[192:195], v147 offset:51200
	ds_read_b128 v[196:199], v147 offset:52224
	ds_read_b128 v[200:203], v147 offset:53248
	ds_read_b128 v[204:207], v147 offset:54272
	ds_read_b128 v[208:211], v147 offset:55296
	ds_read_b128 v[212:215], v147 offset:56320
	global_load_lds_dwordx4 v130, s[36:37] offset:128
	s_add_i32 m0, s10, 0x1f80
	s_add_u32 s10, s36, 0xb0080
	s_addc_u32 s11, s37, 0
	global_load_lds_dwordx4 v134, s[36:37] offset:128
	s_add_i32 s36, s70, s49
	s_mov_b32 m0, s36
	s_nop 0
	global_load_lds_dwordx4 v130, s[10:11]
	s_add_i32 m0, s36, 0x2000
	s_nop 0
	global_load_lds_dwordx4 v134, s[10:11]
	s_add_i32 m0, s57, 0xffffff80
	s_nop 0
	global_load_lds_dwordx4 v128, s[44:45] offset:128
	s_add_i32 m0, s58, 0xffffff80
	s_nop 0
	global_load_lds_dwordx4 v132, s[44:45] offset:128
	s_waitcnt vmcnt(8)
	s_waitcnt lgkmcnt(0)
	s_barrier
	s_setprio 1
	s_waitcnt lgkmcnt(0)
	v_mfma_f32_16x16x32_bf16 v[92:95], v[148:151], v[180:183], v[92:95]
	v_mfma_f32_16x16x32_bf16 v[88:91], v[156:159], v[180:183], v[88:91]
	v_mfma_f32_16x16x32_bf16 v[84:87], v[148:151], v[192:195], v[84:87]
	v_mfma_f32_16x16x32_bf16 v[80:83], v[156:159], v[192:195], v[80:83]
	v_mfma_f32_16x16x32_bf16 v[76:79], v[148:151], v[200:203], v[76:79]
	v_mfma_f32_16x16x32_bf16 v[72:75], v[156:159], v[200:203], v[72:75]
	v_mfma_f32_16x16x32_bf16 v[68:71], v[148:151], v[208:211], v[68:71]
	v_mfma_f32_16x16x32_bf16 v[64:67], v[156:159], v[208:211], v[64:67]
	v_mfma_f32_16x16x32_bf16 v[92:95], v[152:155], v[184:187], v[92:95]
	v_mfma_f32_16x16x32_bf16 v[88:91], v[160:163], v[184:187], v[88:91]
	v_mfma_f32_16x16x32_bf16 v[84:87], v[152:155], v[196:199], v[84:87]
	v_mfma_f32_16x16x32_bf16 v[80:83], v[160:163], v[196:199], v[80:83]
	v_mfma_f32_16x16x32_bf16 v[76:79], v[152:155], v[204:207], v[76:79]
	v_mfma_f32_16x16x32_bf16 v[72:75], v[160:163], v[204:207], v[72:75]
	v_mfma_f32_16x16x32_bf16 v[68:71], v[152:155], v[212:215], v[68:71]
	v_mfma_f32_16x16x32_bf16 v[64:67], v[160:163], v[212:215], v[64:67]
	s_setprio 0
	s_setprio 1
	v_mfma_f32_16x16x32_bf16 v[28:31], v[164:167], v[180:183], v[28:31]
	v_mfma_f32_16x16x32_bf16 v[24:27], v[172:175], v[180:183], v[24:27]
	v_mfma_f32_16x16x32_bf16 v[20:23], v[164:167], v[192:195], v[20:23]
	v_mfma_f32_16x16x32_bf16 v[16:19], v[172:175], v[192:195], v[16:19]
	v_mfma_f32_16x16x32_bf16 v[12:15], v[164:167], v[200:203], v[12:15]
	v_mfma_f32_16x16x32_bf16 v[8:11], v[172:175], v[200:203], v[8:11]
	v_mfma_f32_16x16x32_bf16 v[4:7], v[164:167], v[208:211], v[4:7]
	v_mfma_f32_16x16x32_bf16 v[0:3], v[172:175], v[208:211], v[0:3]
	v_mfma_f32_16x16x32_bf16 v[28:31], v[168:171], v[184:187], v[28:31]
	v_mfma_f32_16x16x32_bf16 v[24:27], v[176:179], v[184:187], v[24:27]
	v_mfma_f32_16x16x32_bf16 v[20:23], v[168:171], v[196:199], v[20:23]
	v_mfma_f32_16x16x32_bf16 v[16:19], v[176:179], v[196:199], v[16:19]
	v_mfma_f32_16x16x32_bf16 v[12:15], v[168:171], v[204:207], v[12:15]
	v_mfma_f32_16x16x32_bf16 v[8:11], v[176:179], v[204:207], v[8:11]
	v_mfma_f32_16x16x32_bf16 v[4:7], v[168:171], v[212:215], v[4:7]
	v_mfma_f32_16x16x32_bf16 v[0:3], v[176:179], v[212:215], v[0:3]
	s_setprio 0
	s_barrier
	s_add_u32 s66, s66, 0x100
	s_addc_u32 s67, s67, 0
	s_cmp_ge_i32 s68, s3
	s_mov_b64 s[10:11], s[28:29]
	s_mov_b32 s36, s68
	s_cbranch_scc0 .LBB0_1117
	s_and_b64 vcc, exec, s[38:39]
	s_cbranch_vccz .LBB0_1120
